# k15
# speedup vs baseline: 1.0091x; 1.0091x over previous
; #define DECODE(t_, z_, pm_, pn_) do { if constexpr (EPI == E_CHDFT) { z_ = (t_) >> 5; pm_ = ((t_) >> 4) & 1; pn_ = (int)sx * 16 + ((t_) & 15); break; } \
;     int wgid = (int)sx * tq + (t_); \
;     z_ = wgid / per; int id = wgid % per; \
;     int nig = WGM * nN, gid = id / nig, fm = gid * WGM, gsz = min(nM - fm, WGM); \
;     pm_ = fm + ((id % nig) % gsz); pn_ = (id % nig) / gsz; } while (0)
; #define STAGE_A(Ak_, b, h) do { const char* _s = (Ak_) + (h) * sHA; \
;     glds16(lds0 + ((b) * 2 + (h)) * (HT * 2), voffA, _s); glds16(lds0 + ((b) * 2 + (h)) * (HT * 2) + 8192, voffA, _s + s2A); } while (0)
; #define STAGE_B(Bk_, Bkh_, vh_, b, h) do { const char* _s = (h) ? (Bkh_) : (Bk_); const unsigned _v0 = (h) ? (vh_)[0] : voffB, _v1 = (h) ? (vh_)[1] : voffB; const long _d = (h) ? s2Bh : s2B; \
;     glds16(lds0 + (4 + (b) * 2 + (h)) * (HT * 2), _v0, _s); glds16(lds0 + (4 + (b) * 2 + (h)) * (HT * 2) + 8192, _v1, _s + _d); } while (0)
; #define WAIT_V(n) asm volatile("s_waitcnt vmcnt(" #n ")" ::: "memory")
; template <int EPI>
; __device__ __forceinline__ void gemm_phase(const GemmDesc d, u16* shm, unsigned sx, unsigned srank, unsigned snloc) {
;     ...
;     int z, pm, pn; const char *Au, *Bu, *Buh; unsigned voffBh[2];
;     DECODE(t, z, pm, pn); BASES(z, pm, pn, Au, Bu, Buh, voffBh);
;     ...
;     WAIT_V(0);
;     STAGE_B(Bu, Buh, voffBh, 0, 0); STAGE_A(Au, 0, 0); STAGE_B(Bu, Buh, voffBh, 0, 1); STAGE_A(Au, 0, 1);
;     if constexpr (NEED_R) {
;       if (tid < 256) {
;         float rv = rsqrtf(SS_ROW(d.ss + (size_t)R_ROW(pm, pn, tid) * 16) * (1.0f / DM) + EPS);
;         lds_r[tid] = R_ZERO(pn, tid) ? 0.f : rv;
;       }
;     ...
;       float* stg = (float*)((char*)shm + GEMM_LDS + 2048 + wid2 * 2304);
;       const float* lr = lds_r + (it & 1) * 256;
;       const int rl = lane2 >> 3, c4 = (lane2 & 7) * 4;
;       if constexpr (EPI == E_SWIGLU) {
;         using f32x2 = __attribute__((ext_vector_type(2))) float;
;         const int sw_row = lane2 >> 2, sw_c8 = (lane2 & 3) * 8;
;         u16* sw_base = d.outb + ((size_t)(brow >> 7) * 44 + pn * 2 + (wc2 >> 1)) * 8192
;                      + ((((sw_row * 64 + sw_c8 * 2) ^ ((sw_row >> 3) << 5)) + (wr2 * 8 + (wc2 & 1)) * 1024) >> 1);
.LBB0_1435:
	v_readlane_b32 s0, v239, 9
	v_readlane_b32 s1, v239, 20
	s_andn2_b64 vcc, exec, s[2:3]
	s_or_b32 s54, s1, s0
	s_cbranch_vccnz .LBB0_1523
	v_readlane_b32 s0, v240, 2
	v_readlane_b32 s1, v240, 3
	s_waitcnt vmcnt(1)
	v_mov_b32_e32 v0, v182
	v_writelane_b32 v240, s0, 2
	s_nop 0
	v_ashrrev_i32_e32 v1, 6, v0
	v_writelane_b32 v240, s1, 3
	v_readlane_b32 s0, v238, 24
	v_readlane_b32 s1, v238, 25
	s_andn2_b64 vcc, exec, s[0:1]
	v_readfirstlane_b32 s4, v1
	s_cbranch_vccnz .LBB0_1457
	v_lshrrev_b32_e32 v245, 6, v182
	v_mul_u32_u24_e32 v246, 0x900, v245
	v_add_u32_e32 v246, s83, v246
	v_bfe_u32 v247, v182, 2, 4
	v_mul_u32_u24_e32 v241, 0x90, v247
	v_add_u32_e32 v241, v246, v241
	v_lshlrev_b32_e32 v244, 3, v182
	v_and_b32_e32 v244, 24, v244
	v_lshl_add_u32 v241, v244, 2, v241
	v_lshlrev_b32_e32 v243, 6, v247
	v_lshlrev_b32_e32 v244, 1, v244
	v_and_b32_e32 v242, 32, v182
	v_bitop3_b32 v243, v243, v242, v244 bitop3:0x36
	v_lshlrev_b32_e32 v244, 5, v182
	v_and_b32_e32 v244, 0xffffe000, v244
	v_lshlrev_b32_e32 v242, 10, v245
	v_and_b32_e32 v242, 0x400, v242
	v_or3_b32 v244, v242, v244, v243
	v_and_b32_e32 v244, -2, v244
	v_lshrrev_b32_e32 v242, 1, v245
	v_and_b32_e32 v242, 1, v242
	v_lshl_add_u32 v244, v242, 14, v244
	v_lshlrev_b32_e32 v242, 2, v182
	v_and_b32_e32 v242, 60, v242
	v_add_u32_e32 v242, v246, v242
	v_lshrrev_b32_e32 v243, 2, v182
	v_and_b32_e32 v243, 12, v243
	v_mul_u32_u24_e32 v247, 0x90, v243
	v_add_u32_e32 v242, v242, v247
	v_and_b32_e32 v247, 0xffffff00, v182
	v_lshl_add_u32 v243, v243, 2, v247
	v_readlane_b32 s0, v240, 2
	v_readlane_b32 s1, v240, 3
	s_load_dwordx2 s[2:3], s[0:1], 0xa8
	s_mul_i32 s6, s54, 0x580000
	s_mov_b32 s7, s36
	s_lshl_b64 s[6:7], s[6:7], 1
	v_bfe_i32 v4, v0, 27, 1
	s_waitcnt lgkmcnt(0)
	s_add_u32 s0, s2, s6
	s_addc_u32 s1, s3, s7
	s_add_u32 s55, s0, 0xf000000
	v_lshlrev_b32_e32 v2, 4, v0
	s_addc_u32 s57, s1, 0
	v_lshrrev_b32_e32 v4, 22, v4
	s_add_u32 s10, s2, 0x17d00000
	v_add_u32_e32 v4, v2, v4
	s_addc_u32 s11, s3, 0
	v_and_b32_e32 v4, 0xfffffc00, v4
	s_lshl_b32 s14, s4, 10
	v_sub_u32_e32 v2, v2, v4
	s_cmp_lg_u32 0, -1
	v_lshrrev_b32_e32 v4, 4, v2
	s_cselect_b32 s0, 0, 0
	v_bitop3_b32 v4, v4, v2, 32 bitop3:0x6c
	v_ashrrev_i32_e32 v2, 31, v2
	s_add_i32 s59, s14, s0
	v_readlane_b32 s0, v238, 48
	v_ashrrev_i32_e32 v3, 31, v0
	v_lshrrev_b32_e32 v2, 26, v2
	v_readlane_b32 s1, v238, 49
	s_add_u32 s34, s2, s0
	v_lshrrev_b32_e32 v3, 26, v3
	v_add_u32_e32 v2, v4, v2
	s_addc_u32 s35, s3, s1
	v_readlane_b32 s0, v238, 30
	v_add_u32_e32 v3, v0, v3
	v_ashrrev_i32_e32 v2, 6, v2
	v_readlane_b32 s1, v238, 31
	s_add_u32 s38, s55, s0
	v_ashrrev_i32_e32 v3, 6, v3
	v_mul_i32_i24_e32 v6, 64, v2
	s_addc_u32 s39, s57, s1
	v_lshlrev_b32_e32 v5, 3, v3
	v_lshlrev_b32_e32 v3, 5, v3
	v_sub_u32_e32 v4, v4, v6
	s_add_u32 s4, s38, 0x40000
	v_and_b32_e32 v5, 0x1ffff0, v5
	v_and_b32_e32 v3, 32, v3
	v_ashrrev_i16_sdwa v4, v187, sext(v4) dst_sel:DWORD dst_unused:UNUSED_PAD src0_sel:DWORD src1_sel:BYTE_0
	s_addc_u32 s5, s39, 0
	s_add_i32 s62, s59, 0x10000
	s_add_i32 s63, s59, 0x12000
	v_add_u32_sdwa v3, v3, sext(v4) dst_sel:DWORD dst_unused:UNUSED_PAD src0_sel:DWORD src1_sel:WORD_0
	v_add_lshl_u32 v2, v2, v5, 11
	s_waitcnt vmcnt(0)
	s_add_u32 s6, s38, 0x20000
	v_lshl_add_u32 v130, v3, 1, v2
	s_mov_b32 m0, s62
	s_nop 0
	global_load_lds_dwordx4 v130, s[38:39]
	s_addc_u32 s7, s39, 0
	s_add_i32 s64, s59, 0x2000
	s_mov_b32 m0, s63
	s_nop 0
	global_load_lds_dwordx4 v130, s[6:7]
	s_add_u32 s6, s34, 0x20000
	s_mov_b32 m0, s59
	s_nop 0
	global_load_lds_dwordx4 v130, s[34:35]
	s_addc_u32 s7, s35, 0
	s_add_i32 s65, s59, 0x14000
	s_add_i32 s66, s59, 0x16000
	s_mov_b32 m0, s64
	s_nop 0
	global_load_lds_dwordx4 v130, s[6:7]
	s_add_u32 s6, s38, 0x60000
	s_mov_b32 m0, s65
	s_nop 0
	global_load_lds_dwordx4 v130, s[4:5]
	s_addc_u32 s7, s39, 0
	s_mov_b32 m0, s66
	s_nop 0
	global_load_lds_dwordx4 v130, s[6:7]
	s_add_u32 s6, s34, 0x40000
	s_addc_u32 s7, s35, 0
	s_add_i32 s67, s59, 0x4000
	s_add_i32 s69, s59, 0x6000
	s_mov_b32 m0, s67
	s_nop 0
	global_load_lds_dwordx4 v130, s[6:7]
	s_add_u32 s6, s34, 0x60000
	s_addc_u32 s7, s35, 0
	s_mov_b32 m0, s69
	s_nop 0
	global_load_lds_dwordx4 v130, s[6:7]
	v_cmp_gt_i32_e32 vcc, s58, v0
	s_and_saveexec_b64 s[6:7], vcc
	s_cbranch_execz .LBB0_1439
	v_readlane_b32 s0, v238, 46
	v_readlane_b32 s1, v238, 47
	s_nop 0
	v_add_u32_e32 v2, s0, v0
	v_ashrrev_i32_e32 v3, 31, v2
	v_lshlrev_b64 v[2:3], 6, v[2:3]
	v_lshl_add_u64 v[14:15], s[10:11], 0, v[2:3]
	global_load_dwordx4 v[2:5], v[14:15], off
	global_load_dwordx4 v[6:9], v[14:15], off offset:16
	global_load_dwordx4 v[10:13], v[14:15], off offset:32
	s_nop 0
	global_load_dwordx4 v[14:17], v[14:15], off offset:48
	s_waitcnt vmcnt(3)
	v_mov_b32_e32 v18, v2
	s_waitcnt vmcnt(2)
	v_mov_b32_e32 v19, v6
	v_mov_b32_e32 v6, v3
	v_mov_b32_e32 v2, v4
	v_mov_b32_e32 v3, v8
	v_mov_b32_e32 v8, v5
	s_waitcnt vmcnt(1)
	v_mov_b32_e32 v4, v10
	s_waitcnt vmcnt(0)
	v_mov_b32_e32 v5, v14
	v_mov_b32_e32 v14, v11
	v_pk_add_f32 v[6:7], v[18:19], v[6:7]
	v_mov_b32_e32 v10, v12
	v_mov_b32_e32 v11, v16
	v_pk_add_f32 v[4:5], v[4:5], v[14:15]
	v_pk_add_f32 v[2:3], v[2:3], v[6:7]
	v_mov_b32_e32 v16, v13
	v_pk_add_f32 v[4:5], v[10:11], v[4:5]
	v_pk_add_f32 v[2:3], v[8:9], v[2:3]
	v_pk_add_f32 v[4:5], v[16:17], v[4:5]
	v_add_f32_e32 v2, v2, v3
	v_add_f32_e32 v2, v2, v4
	v_add_f32_e32 v2, v2, v5
	v_fmamk_f32 v2, v2, 0x3a800000, v186
	v_mov_b32_e32 v5, v2
	v_mul_f32_e32 v3, 0x4b800000, v2
	v_cmp_gt_f32_e32 vcc, s31, v2
	s_nop 1
	v_cndmask_b32_e32 v2, v2, v3, vcc
	v_rsq_f32_e32 v2, v2
	v_lshl_add_u32 v3, v0, 2, 0
	v_add_u32_e32 v3, 0x20000, v3
	v_mul_f32_e32 v4, 0x45800000, v2
	v_cndmask_b32_e32 v2, v2, v4, vcc
	v_mul_f32_e32 v2, s86, v2
	ds_write_b32 v3, v2
	ds_write_b32 v3, v5 offset:20480

; __device__ __forceinline__ unsigned pack2(float lo, float hi) { unsigned r; asm volatile("v_cvt_pk_bf16_f32 %0, %1, %2" : "=v"(r) : "v"(lo), "v"(hi)); return r; }
; template <int EPI>
; __device__ __forceinline__ void gemm_phase(const GemmDesc d, u16* shm, unsigned sx, unsigned srank, unsigned snloc) {
;     ...
;       float* stg = (float*)((char*)shm + GEMM_LDS + 2048 + wid2 * 2304);
;       const float* lr = lds_r + (it & 1) * 256;
;       const int rl = lane2 >> 3, c4 = (lane2 & 7) * 4;
;       if constexpr (EPI == E_SWIGLU) {
;         using f32x2 = __attribute__((ext_vector_type(2))) float;
;         const int sw_row = lane2 >> 2, sw_c8 = (lane2 & 3) * 8;
;         u16* sw_base = d.outb + ((size_t)(brow >> 7) * 44 + pn * 2 + (wc2 >> 1)) * 8192
;                      + ((((sw_row * 64 + sw_c8 * 2) ^ ((sw_row >> 3) << 5)) + (wr2 * 8 + (wc2 & 1)) * 1024) >> 1);
; #pragma unroll
;         for (int ai = 0; ai < 2; ++ai)
; #pragma unroll
;           for (int m = 0; m < 4; ++m) {
;             const f32x4 r4 = *(const f32x4*)&lr[ai * 128 + wr2 * 64 + m * 16 + fq2 * 4];
;             const f32x4 rc4 = r4 * (-1.4426950408889634f), rr4 = r4 * r4;
; #pragma unroll
;             for (int n = 0; n < 2; ++n)
; #pragma unroll
;               for (int jp = 0; jp < 4; jp += 2) {
;                 const f32x2 a = {acc[ai][0][m][n][jp], acc[ai][0][m][n][jp + 1]}, b = {acc[ai][1][m][n][jp], acc[ai][1][m][n][jp + 1]};
;                 const f32x2 rc = {rc4[jp], rc4[jp + 1]}, rr = {rr4[jp], rr4[jp + 1]};
;                 const f32x2 tl = a * rc;
;                 f32x2 dd = {__builtin_amdgcn_exp2f(tl[0]), __builtin_amdgcn_exp2f(tl[1])};
;                 dd = dd + 1.0f;
;                 const f32x2 s = {__builtin_amdgcn_rcpf(dd[0]), __builtin_amdgcn_rcpf(dd[1])};
;                 const f32x2 o = (a * b) * (rr * s);
;                 stg[(fq2 * 4 + jp) * 36 + n * 16 + fr2] = o[0];
;                 stg[(fq2 * 4 + jp + 1) * 36 + n * 16 + fr2] = o[1];
;               }
;             {
;               const f32x4 v0 = *(const f32x4*)&stg[sw_row * 36 + sw_c8], v1 = *(const f32x4*)&stg[sw_row * 36 + sw_c8 + 4];
;               u32x4 w = {pack2(v0[0], v0[1]), pack2(v0[2], v0[3]), pack2(v1[0], v1[1]), pack2(v1[2], v1[3])};
;               __builtin_nontemporal_store(w, (u32x4*)(sw_base + (size_t)ai * (44 * 8192) + m * 1024));
;             }
.LBB0_1452:
	s_or_b64 exec, exec, s[4:5]
	s_lshl_b32 s0, s70, 8
	s_and_b32 s18, s0, 0x100
	s_lshl_b32 s0, s18, 2
	s_add_i32 s0, s0, 0x20000
	v_add_u32_e32 v142, s0, v243
	s_mul_i32 s4, s89, 0x58
	s_lshl_b32 s5, s88, 1
	s_add_u32 s4, s4, s5
	s_mov_b32 s5, 0
	s_lshl_b64 s[4:5], s[4:5], 14
	s_add_u32 s4, s12, s4
	s_addc_u32 s5, s13, s5
	ds_read_b128 v[150:153], v142
	ds_read_b128 v[158:161], v142 offset:20480
	ds_read_b128 v[154:157], v142 offset:64
	ds_read_b128 v[162:165], v142 offset:20544
	s_add_u32 s40, s4, 0x1000
	s_addc_u32 s41, s5, 0
	v_pk_mul_f32 v[120:121], v[124:125], v[120:121]
	v_pk_mul_f32 v[122:123], v[126:127], v[122:123]
	s_add_u32 s22, s4, 0xb0000
	s_addc_u32 s23, s5, 0
	v_pk_mul_f32 v[112:113], v[116:117], v[112:113]
	v_pk_mul_f32 v[114:115], v[118:119], v[114:115]
	s_add_u32 s96, s4, 0xb1000
	s_addc_u32 s97, s5, 0
	s_waitcnt lgkmcnt(2)
	v_pk_mul_f32 v[124:125], v[124:125], v[150:151]
	v_pk_mul_f32 v[126:127], v[126:127], v[152:153]
	v_pk_mul_f32 v[116:117], v[116:117], v[150:151]
	v_pk_mul_f32 v[118:119], v[118:119], v[152:153]
	v_exp_f32_e32 v124, v124
	v_exp_f32_e32 v125, v125
	v_exp_f32_e32 v126, v126
	v_exp_f32_e32 v127, v127
	v_exp_f32_e32 v116, v116
	v_exp_f32_e32 v117, v117
	v_exp_f32_e32 v118, v118
	v_exp_f32_e32 v119, v119
	v_pk_mul_f32 v[104:105], v[108:109], v[104:105]
	v_pk_mul_f32 v[106:107], v[110:111], v[106:107]
	v_pk_mul_f32 v[96:97], v[100:101], v[96:97]
	v_pk_mul_f32 v[98:99], v[102:103], v[98:99]
	v_pk_fma_f32 v[124:125], v[124:125], v[158:159], v[158:159]
	v_pk_fma_f32 v[126:127], v[126:127], v[160:161], v[160:161]
	v_pk_fma_f32 v[116:117], v[116:117], v[158:159], v[158:159]
	v_pk_fma_f32 v[118:119], v[118:119], v[160:161], v[160:161]
	v_rcp_f32_e32 v124, v124
	v_rcp_f32_e32 v125, v125
	v_rcp_f32_e32 v126, v126
	v_rcp_f32_e32 v127, v127
	v_rcp_f32_e32 v116, v116
	v_rcp_f32_e32 v117, v117
	v_rcp_f32_e32 v118, v118
	v_rcp_f32_e32 v119, v119
	v_pk_mul_f32 v[120:121], v[120:121], v[124:125]
	v_pk_mul_f32 v[122:123], v[122:123], v[126:127]
	v_pk_mul_f32 v[112:113], v[112:113], v[116:117]
	v_pk_mul_f32 v[114:115], v[114:115], v[118:119]
	ds_write2_b32 v242, v120, v112 offset1:16
	ds_write2_b32 v242, v121, v113 offset0:36 offset1:52
	ds_write2_b32 v242, v122, v114 offset0:72 offset1:88
	ds_write2_b32 v242, v123, v115 offset0:108 offset1:124
	ds_read_b128 v[166:169], v241
	ds_read_b128 v[170:173], v241 offset:16
	ds_read_b128 v[150:153], v142 offset:128
	ds_read_b128 v[158:161], v142 offset:20608
	s_waitcnt lgkmcnt(8)
	v_pk_mul_f32 v[108:109], v[108:109], v[154:155]
	v_pk_mul_f32 v[110:111], v[110:111], v[156:157]
	v_pk_mul_f32 v[100:101], v[100:101], v[154:155]
	v_pk_mul_f32 v[102:103], v[102:103], v[156:157]
	v_exp_f32_e32 v108, v108
	v_exp_f32_e32 v109, v109
	v_exp_f32_e32 v110, v110
	v_exp_f32_e32 v111, v111
	v_exp_f32_e32 v100, v100
	v_exp_f32_e32 v101, v101
	v_exp_f32_e32 v102, v102
	v_exp_f32_e32 v103, v103
	v_pk_mul_f32 v[88:89], v[92:93], v[88:89]
	v_pk_mul_f32 v[90:91], v[94:95], v[90:91]
	v_pk_mul_f32 v[80:81], v[84:85], v[80:81]
	v_pk_mul_f32 v[82:83], v[86:87], v[82:83]
	s_waitcnt lgkmcnt(2)
	v_cvt_pk_bf16_f32 v166, v166, v167
	v_cvt_pk_bf16_f32 v167, v168, v169
	v_cvt_pk_bf16_f32 v168, v170, v171
	v_cvt_pk_bf16_f32 v169, v172, v173
	global_store_dwordx4 v244, v[166:169], s[4:5] nt
	v_pk_fma_f32 v[108:109], v[108:109], v[162:163], v[162:163]
	v_pk_fma_f32 v[110:111], v[110:111], v[164:165], v[164:165]
	v_pk_fma_f32 v[100:101], v[100:101], v[162:163], v[162:163]
	v_pk_fma_f32 v[102:103], v[102:103], v[164:165], v[164:165]
	v_rcp_f32_e32 v108, v108
	v_rcp_f32_e32 v109, v109
	v_rcp_f32_e32 v110, v110
	v_rcp_f32_e32 v111, v111
	v_rcp_f32_e32 v100, v100
	v_rcp_f32_e32 v101, v101
	v_rcp_f32_e32 v102, v102
	v_rcp_f32_e32 v103, v103
	v_pk_mul_f32 v[104:105], v[104:105], v[108:109]
	v_pk_mul_f32 v[106:107], v[106:107], v[110:111]
	v_pk_mul_f32 v[96:97], v[96:97], v[100:101]
	v_pk_mul_f32 v[98:99], v[98:99], v[102:103]
	ds_write2_b32 v242, v104, v96 offset1:16
	ds_write2_b32 v242, v105, v97 offset0:36 offset1:52
	ds_write2_b32 v242, v106, v98 offset0:72 offset1:88
	ds_write2_b32 v242, v107, v99 offset0:108 offset1:124
	ds_read_b128 v[190:193], v241
	ds_read_b128 v[194:197], v241 offset:16
	ds_read_b128 v[154:157], v142 offset:192
	ds_read_b128 v[162:165], v142 offset:20672
	s_waitcnt lgkmcnt(8)
	v_pk_mul_f32 v[92:93], v[92:93], v[150:151]
	v_pk_mul_f32 v[94:95], v[94:95], v[152:153]
	v_pk_mul_f32 v[84:85], v[84:85], v[150:151]
	v_pk_mul_f32 v[86:87], v[86:87], v[152:153]
	v_exp_f32_e32 v92, v92
	v_exp_f32_e32 v93, v93
	v_exp_f32_e32 v94, v94
	v_exp_f32_e32 v95, v95
	v_exp_f32_e32 v84, v84
	v_exp_f32_e32 v85, v85
	v_exp_f32_e32 v86, v86
	v_exp_f32_e32 v87, v87
	v_pk_mul_f32 v[72:73], v[76:77], v[72:73]
	v_pk_mul_f32 v[74:75], v[78:79], v[74:75]
	v_pk_mul_f32 v[64:65], v[68:69], v[64:65]
	v_pk_mul_f32 v[66:67], v[70:71], v[66:67]
	s_waitcnt lgkmcnt(2)
	v_cvt_pk_bf16_f32 v190, v190, v191
	v_cvt_pk_bf16_f32 v191, v192, v193
	v_cvt_pk_bf16_f32 v192, v194, v195
	v_cvt_pk_bf16_f32 v193, v196, v197
	global_store_dwordx4 v244, v[190:193], s[4:5] offset:2048 nt
	v_pk_fma_f32 v[92:93], v[92:93], v[158:159], v[158:159]
	v_pk_fma_f32 v[94:95], v[94:95], v[160:161], v[160:161]
	v_pk_fma_f32 v[84:85], v[84:85], v[158:159], v[158:159]
	v_pk_fma_f32 v[86:87], v[86:87], v[160:161], v[160:161]
	v_rcp_f32_e32 v92, v92
	v_rcp_f32_e32 v93, v93
	v_rcp_f32_e32 v94, v94
	v_rcp_f32_e32 v95, v95
	v_rcp_f32_e32 v84, v84
	v_rcp_f32_e32 v85, v85
	v_rcp_f32_e32 v86, v86
	v_rcp_f32_e32 v87, v87
	v_pk_mul_f32 v[88:89], v[88:89], v[92:93]
	v_pk_mul_f32 v[90:91], v[90:91], v[94:95]
	v_pk_mul_f32 v[80:81], v[80:81], v[84:85]
	v_pk_mul_f32 v[82:83], v[82:83], v[86:87]
	ds_write2_b32 v242, v88, v80 offset1:16
	ds_write2_b32 v242, v89, v81 offset0:36 offset1:52
	ds_write2_b32 v242, v90, v82 offset0:72 offset1:88
	ds_write2_b32 v242, v91, v83 offset0:108 offset1:124
	ds_read_b128 v[166:169], v241
	ds_read_b128 v[170:173], v241 offset:16
	ds_read_b128 v[150:153], v142 offset:512
	ds_read_b128 v[158:161], v142 offset:20992
	s_waitcnt lgkmcnt(8)
; __device__ __forceinline__ unsigned pack2(float lo, float hi) { unsigned r; asm volatile("v_cvt_pk_bf16_f32 %0, %1, %2" : "=v"(r) : "v"(lo), "v"(hi)); return r; }
; template <int EPI>
; __device__ __forceinline__ void gemm_phase(const GemmDesc d, u16* shm, unsigned sx, unsigned srank, unsigned snloc) {
;     ...
;         for (int ai = 0; ai < 2; ++ai)
; #pragma unroll
;           for (int m = 0; m < 4; ++m) {
;             const f32x4 r4 = *(const f32x4*)&lr[ai * 128 + wr2 * 64 + m * 16 + fq2 * 4];
;             const f32x4 rc4 = r4 * (-1.4426950408889634f), rr4 = r4 * r4;
; #pragma unroll
;             for (int n = 0; n < 2; ++n)
; #pragma unroll
;               for (int jp = 0; jp < 4; jp += 2) {
;                 const f32x2 a = {acc[ai][0][m][n][jp], acc[ai][0][m][n][jp + 1]}, b = {acc[ai][1][m][n][jp], acc[ai][1][m][n][jp + 1]};
;                 const f32x2 rc = {rc4[jp], rc4[jp + 1]}, rr = {rr4[jp], rr4[jp + 1]};
;                 const f32x2 tl = a * rc;
;                 f32x2 dd = {__builtin_amdgcn_exp2f(tl[0]), __builtin_amdgcn_exp2f(tl[1])};
;                 dd = dd + 1.0f;
;                 const f32x2 s = {__builtin_amdgcn_rcpf(dd[0]), __builtin_amdgcn_rcpf(dd[1])};
;                 const f32x2 o = (a * b) * (rr * s);
;                 stg[(fq2 * 4 + jp) * 36 + n * 16 + fr2] = o[0];
;                 stg[(fq2 * 4 + jp + 1) * 36 + n * 16 + fr2] = o[1];
;               }
;             {
;               const f32x4 v0 = *(const f32x4*)&stg[sw_row * 36 + sw_c8], v1 = *(const f32x4*)&stg[sw_row * 36 + sw_c8 + 4];
;               u32x4 w = {pack2(v0[0], v0[1]), pack2(v0[2], v0[3]), pack2(v1[0], v1[1]), pack2(v1[2], v1[3])};
;               __builtin_nontemporal_store(w, (u32x4*)(sw_base + (size_t)ai * (44 * 8192) + m * 1024));
;             }
	v_pk_mul_f32 v[76:77], v[76:77], v[154:155]
	v_pk_mul_f32 v[78:79], v[78:79], v[156:157]
	v_pk_mul_f32 v[68:69], v[68:69], v[154:155]
	v_pk_mul_f32 v[70:71], v[70:71], v[156:157]
	v_exp_f32_e32 v76, v76
	v_exp_f32_e32 v77, v77
	v_exp_f32_e32 v78, v78
	v_exp_f32_e32 v79, v79
	v_exp_f32_e32 v68, v68
	v_exp_f32_e32 v69, v69
	v_exp_f32_e32 v70, v70
	v_exp_f32_e32 v71, v71
	v_pk_mul_f32 v[56:57], v[60:61], v[56:57]
	v_pk_mul_f32 v[58:59], v[62:63], v[58:59]
	v_pk_mul_f32 v[48:49], v[52:53], v[48:49]
	v_pk_mul_f32 v[50:51], v[54:55], v[50:51]
	s_waitcnt lgkmcnt(2)
	v_cvt_pk_bf16_f32 v166, v166, v167
	v_cvt_pk_bf16_f32 v167, v168, v169
	v_cvt_pk_bf16_f32 v168, v170, v171
	v_cvt_pk_bf16_f32 v169, v172, v173
	global_store_dwordx4 v244, v[166:169], s[40:41] nt
	v_pk_fma_f32 v[76:77], v[76:77], v[162:163], v[162:163]
	v_pk_fma_f32 v[78:79], v[78:79], v[164:165], v[164:165]
	v_pk_fma_f32 v[68:69], v[68:69], v[162:163], v[162:163]
	v_pk_fma_f32 v[70:71], v[70:71], v[164:165], v[164:165]
	v_rcp_f32_e32 v76, v76
	v_rcp_f32_e32 v77, v77
	v_rcp_f32_e32 v78, v78
	v_rcp_f32_e32 v79, v79
	v_rcp_f32_e32 v68, v68
	v_rcp_f32_e32 v69, v69
	v_rcp_f32_e32 v70, v70
	v_rcp_f32_e32 v71, v71
	v_pk_mul_f32 v[72:73], v[72:73], v[76:77]
	v_pk_mul_f32 v[74:75], v[74:75], v[78:79]
	v_pk_mul_f32 v[64:65], v[64:65], v[68:69]
	v_pk_mul_f32 v[66:67], v[66:67], v[70:71]
	ds_write2_b32 v242, v72, v64 offset1:16
	ds_write2_b32 v242, v73, v65 offset0:36 offset1:52
	ds_write2_b32 v242, v74, v66 offset0:72 offset1:88
	ds_write2_b32 v242, v75, v67 offset0:108 offset1:124
	ds_read_b128 v[190:193], v241
	ds_read_b128 v[194:197], v241 offset:16
	ds_read_b128 v[154:157], v142 offset:576
	ds_read_b128 v[162:165], v142 offset:21056
	s_waitcnt lgkmcnt(8)
	v_pk_mul_f32 v[60:61], v[60:61], v[150:151]
	v_pk_mul_f32 v[62:63], v[62:63], v[152:153]
	v_pk_mul_f32 v[52:53], v[52:53], v[150:151]
	v_pk_mul_f32 v[54:55], v[54:55], v[152:153]
	v_exp_f32_e32 v60, v60
	v_exp_f32_e32 v61, v61
	v_exp_f32_e32 v62, v62
	v_exp_f32_e32 v63, v63
	v_exp_f32_e32 v52, v52
	v_exp_f32_e32 v53, v53
	v_exp_f32_e32 v54, v54
	v_exp_f32_e32 v55, v55
	v_pk_mul_f32 v[40:41], v[44:45], v[40:41]
	v_pk_mul_f32 v[42:43], v[46:47], v[42:43]
	v_pk_mul_f32 v[32:33], v[36:37], v[32:33]
	v_pk_mul_f32 v[34:35], v[38:39], v[34:35]
	s_waitcnt lgkmcnt(2)
	v_cvt_pk_bf16_f32 v190, v190, v191
	v_cvt_pk_bf16_f32 v191, v192, v193
	v_cvt_pk_bf16_f32 v192, v194, v195
	v_cvt_pk_bf16_f32 v193, v196, v197
	global_store_dwordx4 v244, v[190:193], s[40:41] offset:2048 nt
	v_pk_fma_f32 v[60:61], v[60:61], v[158:159], v[158:159]
	v_pk_fma_f32 v[62:63], v[62:63], v[160:161], v[160:161]
	v_pk_fma_f32 v[52:53], v[52:53], v[158:159], v[158:159]
	v_pk_fma_f32 v[54:55], v[54:55], v[160:161], v[160:161]
	v_rcp_f32_e32 v60, v60
	v_rcp_f32_e32 v61, v61
	v_rcp_f32_e32 v62, v62
	v_rcp_f32_e32 v63, v63
	v_rcp_f32_e32 v52, v52
	v_rcp_f32_e32 v53, v53
	v_rcp_f32_e32 v54, v54
	v_rcp_f32_e32 v55, v55
	v_pk_mul_f32 v[56:57], v[56:57], v[60:61]
	v_pk_mul_f32 v[58:59], v[58:59], v[62:63]
	v_pk_mul_f32 v[48:49], v[48:49], v[52:53]
	v_pk_mul_f32 v[50:51], v[50:51], v[54:55]
	ds_write2_b32 v242, v56, v48 offset1:16
	ds_write2_b32 v242, v57, v49 offset0:36 offset1:52
	ds_write2_b32 v242, v58, v50 offset0:72 offset1:88
	ds_write2_b32 v242, v59, v51 offset0:108 offset1:124
	ds_read_b128 v[166:169], v241
	ds_read_b128 v[170:173], v241 offset:16
	ds_read_b128 v[150:153], v142 offset:640
	ds_read_b128 v[158:161], v142 offset:21120
	s_waitcnt lgkmcnt(8)
	v_pk_mul_f32 v[44:45], v[44:45], v[154:155]
	v_pk_mul_f32 v[46:47], v[46:47], v[156:157]
	v_pk_mul_f32 v[36:37], v[36:37], v[154:155]
	v_pk_mul_f32 v[38:39], v[38:39], v[156:157]
	v_exp_f32_e32 v44, v44
	v_exp_f32_e32 v45, v45
	v_exp_f32_e32 v46, v46
	v_exp_f32_e32 v47, v47
	v_exp_f32_e32 v36, v36
	v_exp_f32_e32 v37, v37
	v_exp_f32_e32 v38, v38
	v_exp_f32_e32 v39, v39
	v_pk_mul_f32 v[24:25], v[28:29], v[24:25]
	v_pk_mul_f32 v[26:27], v[30:31], v[26:27]
	v_pk_mul_f32 v[16:17], v[20:21], v[16:17]
	v_pk_mul_f32 v[18:19], v[22:23], v[18:19]
	s_waitcnt lgkmcnt(2)
; __device__ __forceinline__ unsigned pack2(float lo, float hi) { unsigned r; asm volatile("v_cvt_pk_bf16_f32 %0, %1, %2" : "=v"(r) : "v"(lo), "v"(hi)); return r; }
; template <int EPI>
; __device__ __forceinline__ void gemm_phase(const GemmDesc d, u16* shm, unsigned sx, unsigned srank, unsigned snloc) {
;     ...
;         for (int ai = 0; ai < 2; ++ai)
; #pragma unroll
;           for (int m = 0; m < 4; ++m) {
;             const f32x4 r4 = *(const f32x4*)&lr[ai * 128 + wr2 * 64 + m * 16 + fq2 * 4];
;             const f32x4 rc4 = r4 * (-1.4426950408889634f), rr4 = r4 * r4;
; #pragma unroll
;             for (int n = 0; n < 2; ++n)
; #pragma unroll
;               for (int jp = 0; jp < 4; jp += 2) {
;                 const f32x2 a = {acc[ai][0][m][n][jp], acc[ai][0][m][n][jp + 1]}, b = {acc[ai][1][m][n][jp], acc[ai][1][m][n][jp + 1]};
;                 const f32x2 rc = {rc4[jp], rc4[jp + 1]}, rr = {rr4[jp], rr4[jp + 1]};
;                 const f32x2 tl = a * rc;
;                 f32x2 dd = {__builtin_amdgcn_exp2f(tl[0]), __builtin_amdgcn_exp2f(tl[1])};
;                 dd = dd + 1.0f;
;                 const f32x2 s = {__builtin_amdgcn_rcpf(dd[0]), __builtin_amdgcn_rcpf(dd[1])};
;                 const f32x2 o = (a * b) * (rr * s);
;                 stg[(fq2 * 4 + jp) * 36 + n * 16 + fr2] = o[0];
;                 stg[(fq2 * 4 + jp + 1) * 36 + n * 16 + fr2] = o[1];
;               }
;             {
;               const f32x4 v0 = *(const f32x4*)&stg[sw_row * 36 + sw_c8], v1 = *(const f32x4*)&stg[sw_row * 36 + sw_c8 + 4];
;               u32x4 w = {pack2(v0[0], v0[1]), pack2(v0[2], v0[3]), pack2(v1[0], v1[1]), pack2(v1[2], v1[3])};
;               __builtin_nontemporal_store(w, (u32x4*)(sw_base + (size_t)ai * (44 * 8192) + m * 1024));
;             }
;     ...
;       if constexpr (NEED_R) {
;         if (has_next && t2 < 256) lds_r[((it + 1) & 1) * 256 + t2] = R_ZERO(pnn, t2) ? 0.f : rsqrtf(ssn * (1.0f / DM) + EPS);
	v_cvt_pk_bf16_f32 v166, v166, v167
	v_cvt_pk_bf16_f32 v167, v168, v169
	v_cvt_pk_bf16_f32 v168, v170, v171
	v_cvt_pk_bf16_f32 v169, v172, v173
	global_store_dwordx4 v244, v[166:169], s[22:23] nt
	v_pk_fma_f32 v[44:45], v[44:45], v[162:163], v[162:163]
	v_pk_fma_f32 v[46:47], v[46:47], v[164:165], v[164:165]
	v_pk_fma_f32 v[36:37], v[36:37], v[162:163], v[162:163]
	v_pk_fma_f32 v[38:39], v[38:39], v[164:165], v[164:165]
	v_rcp_f32_e32 v44, v44
	v_rcp_f32_e32 v45, v45
	v_rcp_f32_e32 v46, v46
	v_rcp_f32_e32 v47, v47
	v_rcp_f32_e32 v36, v36
	v_rcp_f32_e32 v37, v37
	v_rcp_f32_e32 v38, v38
	v_rcp_f32_e32 v39, v39
	v_pk_mul_f32 v[40:41], v[40:41], v[44:45]
	v_pk_mul_f32 v[42:43], v[42:43], v[46:47]
	v_pk_mul_f32 v[32:33], v[32:33], v[36:37]
	v_pk_mul_f32 v[34:35], v[34:35], v[38:39]
	ds_write2_b32 v242, v40, v32 offset1:16
	ds_write2_b32 v242, v41, v33 offset0:36 offset1:52
	ds_write2_b32 v242, v42, v34 offset0:72 offset1:88
	ds_write2_b32 v242, v43, v35 offset0:108 offset1:124
	ds_read_b128 v[190:193], v241
	ds_read_b128 v[194:197], v241 offset:16
	ds_read_b128 v[154:157], v142 offset:704
	ds_read_b128 v[162:165], v142 offset:21184
	s_waitcnt lgkmcnt(8)
	v_pk_mul_f32 v[28:29], v[28:29], v[150:151]
	v_pk_mul_f32 v[30:31], v[30:31], v[152:153]
	v_pk_mul_f32 v[20:21], v[20:21], v[150:151]
	v_pk_mul_f32 v[22:23], v[22:23], v[152:153]
	v_exp_f32_e32 v28, v28
	v_exp_f32_e32 v29, v29
	v_exp_f32_e32 v30, v30
	v_exp_f32_e32 v31, v31
	v_exp_f32_e32 v20, v20
	v_exp_f32_e32 v21, v21
	v_exp_f32_e32 v22, v22
	v_exp_f32_e32 v23, v23
	v_pk_mul_f32 v[8:9], v[12:13], v[8:9]
	v_pk_mul_f32 v[10:11], v[14:15], v[10:11]
	v_pk_mul_f32 v[0:1], v[4:5], v[0:1]
	v_pk_mul_f32 v[2:3], v[6:7], v[2:3]
	s_waitcnt lgkmcnt(2)
	v_cvt_pk_bf16_f32 v190, v190, v191
	v_cvt_pk_bf16_f32 v191, v192, v193
	v_cvt_pk_bf16_f32 v192, v194, v195
	v_cvt_pk_bf16_f32 v193, v196, v197
	global_store_dwordx4 v244, v[190:193], s[22:23] offset:2048 nt
	v_pk_fma_f32 v[28:29], v[28:29], v[158:159], v[158:159]
	v_pk_fma_f32 v[30:31], v[30:31], v[160:161], v[160:161]
	v_pk_fma_f32 v[20:21], v[20:21], v[158:159], v[158:159]
	v_pk_fma_f32 v[22:23], v[22:23], v[160:161], v[160:161]
	v_rcp_f32_e32 v28, v28
	v_rcp_f32_e32 v29, v29
	v_rcp_f32_e32 v30, v30
	v_rcp_f32_e32 v31, v31
	v_rcp_f32_e32 v20, v20
	v_rcp_f32_e32 v21, v21
	v_rcp_f32_e32 v22, v22
	v_rcp_f32_e32 v23, v23
	v_pk_mul_f32 v[24:25], v[24:25], v[28:29]
	v_pk_mul_f32 v[26:27], v[26:27], v[30:31]
	v_pk_mul_f32 v[16:17], v[16:17], v[20:21]
	v_pk_mul_f32 v[18:19], v[18:19], v[22:23]
	ds_write2_b32 v242, v24, v16 offset1:16
	ds_write2_b32 v242, v25, v17 offset0:36 offset1:52
	ds_write2_b32 v242, v26, v18 offset0:72 offset1:88
	ds_write2_b32 v242, v27, v19 offset0:108 offset1:124
	ds_read_b128 v[166:169], v241
	ds_read_b128 v[170:173], v241 offset:16
	s_waitcnt lgkmcnt(6)
	v_pk_mul_f32 v[12:13], v[12:13], v[154:155]
	v_pk_mul_f32 v[14:15], v[14:15], v[156:157]
	v_pk_mul_f32 v[4:5], v[4:5], v[154:155]
	v_pk_mul_f32 v[6:7], v[6:7], v[156:157]
	v_exp_f32_e32 v12, v12
	v_exp_f32_e32 v13, v13
	v_exp_f32_e32 v14, v14
	v_exp_f32_e32 v15, v15
	v_exp_f32_e32 v4, v4
	v_exp_f32_e32 v5, v5
	v_exp_f32_e32 v6, v6
	v_exp_f32_e32 v7, v7
	s_waitcnt lgkmcnt(0)
	v_cvt_pk_bf16_f32 v166, v166, v167
	v_cvt_pk_bf16_f32 v167, v168, v169
	v_cvt_pk_bf16_f32 v168, v170, v171
	v_cvt_pk_bf16_f32 v169, v172, v173
	global_store_dwordx4 v244, v[166:169], s[96:97] nt
	v_pk_fma_f32 v[12:13], v[12:13], v[162:163], v[162:163]
	v_pk_fma_f32 v[14:15], v[14:15], v[164:165], v[164:165]
	v_pk_fma_f32 v[4:5], v[4:5], v[162:163], v[162:163]
	v_pk_fma_f32 v[6:7], v[6:7], v[164:165], v[164:165]
	v_rcp_f32_e32 v12, v12
	v_rcp_f32_e32 v13, v13
	v_rcp_f32_e32 v14, v14
	v_rcp_f32_e32 v15, v15
	v_rcp_f32_e32 v4, v4
	v_rcp_f32_e32 v5, v5
	v_rcp_f32_e32 v6, v6
	v_rcp_f32_e32 v7, v7
	v_pk_mul_f32 v[8:9], v[8:9], v[12:13]
	v_pk_mul_f32 v[10:11], v[10:11], v[14:15]
	v_pk_mul_f32 v[0:1], v[0:1], v[4:5]
	v_pk_mul_f32 v[2:3], v[2:3], v[6:7]
	ds_write2_b32 v242, v8, v0 offset1:16
	ds_write2_b32 v242, v9, v1 offset0:36 offset1:52
	ds_write2_b32 v242, v10, v2 offset0:72 offset1:88
	ds_write2_b32 v242, v11, v3 offset0:108 offset1:124
	ds_read_b128 v[190:193], v241
	ds_read_b128 v[194:197], v241 offset:16
	s_waitcnt lgkmcnt(0)
	v_cvt_pk_bf16_f32 v190, v190, v191
	v_cvt_pk_bf16_f32 v191, v192, v193
	v_cvt_pk_bf16_f32 v192, v194, v195
	v_cvt_pk_bf16_f32 v193, v196, v197
	global_store_dwordx4 v244, v[190:193], s[96:97] offset:2048 nt
	s_and_saveexec_b64 s[4:5], s[34:35]
	s_cbranch_execz .LBB0_1454
	v_cmp_gt_f32_e32 vcc, s31, v140
	v_mul_f32_e32 v0, 0x4b800000, v140
	s_xor_b32 s0, s18, 0x100
	v_cndmask_b32_e32 v0, v140, v0, vcc
	v_rsq_f32_e32 v0, v0
	s_lshl_b32 s0, s0, 2
	s_add_i32 s0, s0, 0
	v_mul_f32_e32 v1, 0x45800000, v0
	v_cndmask_b32_e32 v0, v0, v1, vcc
	v_lshl_add_u32 v1, v139, 2, s0
	v_add_u32_e32 v1, 0x20000, v1
	v_mul_f32_e32 v0, s86, v0
	ds_write_b32 v1, v0
	ds_write_b32 v1, v140 offset:20480

; __global__ void __launch_bounds__(NTHREADS, 2) fwd_megakernel(Params p_unused, int ph0, int ph1) {
	.amdhsa_kernel _Z14fwd_megakernel6Paramsii
		.amdhsa_group_segment_fixed_size 2048
		.amdhsa_private_segment_fixed_size 0
		.amdhsa_kernarg_size 440
		.amdhsa_user_sgpr_count 2
		.amdhsa_user_sgpr_dispatch_ptr 0
		.amdhsa_user_sgpr_queue_ptr 0
		.amdhsa_user_sgpr_kernarg_segment_ptr 1
		.amdhsa_user_sgpr_dispatch_id 0
		.amdhsa_user_sgpr_kernarg_preload_length 0
		.amdhsa_user_sgpr_kernarg_preload_offset 0
		.amdhsa_user_sgpr_private_segment_size 0
		.amdhsa_uses_dynamic_stack 0
		.amdhsa_enable_private_segment 0
		.amdhsa_system_sgpr_workgroup_id_x 1
		.amdhsa_system_sgpr_workgroup_id_y 0
		.amdhsa_system_sgpr_workgroup_id_z 0
		.amdhsa_system_sgpr_workgroup_info 0
		.amdhsa_system_vgpr_workitem_id 2
		.amdhsa_next_free_vgpr 248
		.amdhsa_next_free_sgpr 100
		.amdhsa_accum_offset 248
		.amdhsa_reserve_vcc 1
		.amdhsa_float_round_mode_32 0
		.amdhsa_float_round_mode_16_64 0
		.amdhsa_float_denorm_mode_32 3
		.amdhsa_float_denorm_mode_16_64 3
		.amdhsa_dx10_clamp 1
		.amdhsa_ieee_mode 1
		.amdhsa_fp16_overflow 0
		.amdhsa_tg_split 0
		.amdhsa_exception_fp_ieee_invalid_op 0
		.amdhsa_exception_fp_denorm_src 0
		.amdhsa_exception_fp_ieee_div_zero 0
		.amdhsa_exception_fp_ieee_overflow 0
		.amdhsa_exception_fp_ieee_underflow 0
		.amdhsa_exception_fp_ieee_inexact 0
		.amdhsa_exception_int_div_zero 0
	.end_amdhsa_kernel

; __global__ void __launch_bounds__(NTHREADS, 2) fwd_megakernel(Params p_unused, int ph0, int ph1) {
amdhsa.kernels:
  - .agpr_count:     0
    .args:
      - .offset:         0
        .size:           176
        .value_kind:     by_value
      - .offset:         176
        .size:           4
        .value_kind:     by_value
      - .offset:         180
        .size:           4
        .value_kind:     by_value
      - .offset:         184
        .size:           4
        .value_kind:     hidden_block_count_x
      - .offset:         188
        .size:           4
        .value_kind:     hidden_block_count_y
      - .offset:         192
        .size:           4
        .value_kind:     hidden_block_count_z
      - .offset:         196
        .size:           2
        .value_kind:     hidden_group_size_x
      - .offset:         198
        .size:           2
        .value_kind:     hidden_group_size_y
      - .offset:         200
        .size:           2
        .value_kind:     hidden_group_size_z
      - .offset:         202
        .size:           2
        .value_kind:     hidden_remainder_x
      - .offset:         204
        .size:           2
        .value_kind:     hidden_remainder_y
      - .offset:         206
        .size:           2
        .value_kind:     hidden_remainder_z
      - .offset:         224
        .size:           8
        .value_kind:     hidden_global_offset_x
      - .offset:         232
        .size:           8
        .value_kind:     hidden_global_offset_y
      - .offset:         240
        .size:           8
        .value_kind:     hidden_global_offset_z
      - .offset:         248
        .size:           2
        .value_kind:     hidden_grid_dims
      - .offset:         272
        .size:           8
        .value_kind:     hidden_multigrid_sync_arg
      - .offset:         304
        .size:           4
        .value_kind:     hidden_dynamic_lds_size
    .group_segment_fixed_size: 2048
    .kernarg_segment_align: 8
    .kernarg_segment_size: 440
    .language:       OpenCL C
    .language_version:
      - 2
      - 0
    .max_flat_workgroup_size: 512
    .name:           _Z14fwd_megakernel6Paramsii
    .private_segment_fixed_size: 0
    .sgpr_count:     106
    .sgpr_spill_count: 207
    .symbol:         _Z14fwd_megakernel6Paramsii.kd
    .uniform_work_group_size: 1
    .uses_dynamic_stack: false
    .vgpr_count:     248
    .vgpr_spill_count: 0
    .wavefront_size: 64
